# speedup vs baseline: 1.0208x; 1.0091x over previous
; #define PG8_STAGE(bufoff, gbase, voff) do { _Pragma("unroll") for (int _i = 0; _i < 2; ++_i) \
;         __builtin_amdgcn_global_load_lds((const unsigned*)((const char*)(gbase) + (voff)[_i]), (PG8_LAS unsigned*)(lds + (bufoff) + ldsw + _i * 8192), 16, 0, 0); } while (0)
; #define PG8_LDA(dst, b, h) do { _Pragma("unroll") for (int m = 0; m < 4; ++m) _Pragma("unroll") for (int k = 0; k < 2; ++k) dst[m][k] = *(const PG8_LAS bf16x8*)(lds + PG8_SA(b, h) + aoff + m * 2048 + k * 1024); } while (0)
; #define PG8_LDB(dst, b, h) do { _Pragma("unroll") for (int n = 0; n < 2; ++n) _Pragma("unroll") for (int k = 0; k < 2; ++k) dst[n][k] = *(const PG8_LAS bf16x8*)(lds + PG8_SB(b, h) + boff + n * 2048 + k * 1024); } while (0)
; #define PG8_WAIT_V(n) asm volatile("s_waitcnt vmcnt(" #n ")" ::: "memory")
; #define PG8_WAIT_L(n) asm volatile("s_waitcnt lgkmcnt(" #n ")" ::: "memory")
; #define PG8_BAR __builtin_amdgcn_s_barrier()
; __device__ __forceinline__ float row_rstd(const float* part, int row, int fq) {
;     const f32x4* p = (const f32x4*)(part + (size_t)row * 32 + 8 * fq); const f32x4 a = p[0], b = p[1];
;     float s = ((a[0] + a[1]) + (a[2] + a[3])) + ((b[0] + b[1]) + (b[2] + b[3]));
;     s += __shfl_xor(s, 16); s += __shfl_xor(s, 32);
;     return 1.0f / sqrtf(s * (1.0f / 2048.0f) + 1e-6f);
; template <class Epi, class Sched, bool ALIGN_EPI = false, bool SP2 = false>
; __device__ __forceinline__ void gemm_phase(PG8_LAS unsigned char* lds, const Gemm g, const Sched& S, const Epi& E, const int wave_s) {
;     ...
;         for (int t = 0; t < nt; t += 2) {
;             const bool last = (t == nt - 2);
;             const char* a1 = cA + (size_t)(t + 1) * kstep;
;             const char* a2 = last ? nA : cA + (size_t)(t + 2) * kstep; const char* b2 = last ? nB : cB + (size_t)(t + 2) * kstep;
;             const char* a3 = a2 + kstep; const char* b3 = b2 + kstep;
;             if (last && has_next) S.a_ready(nxt);
;             if constexpr (SP2) {
;             PG8_LDB(B0, 0, 0); PG8_LDB(B1, 0, 1); PG8_SCHED; PG8_LDA(At, 0, 0); PG8_STAGE(PG8_SA(1, 1), a1 + hstep, voffA);
;             PG8_WAIT_V(8); PG8_WAIT_L(0); PG8_BAR; PG8_MMA(0, 0, At, B0); PG8_MMA(0, 1, At, B1); PG8_BAR; PG8_SCHED;
;             PG8_LDA(At, 0, 1); PG8_STAGE(PG8_SB(0, 0), b2, voffB); PG8_STAGE(PG8_SB(0, 1), b2 + hstep, voffB); PG8_STAGE(PG8_SA(0, 0), a2, voffA);
.LBB0_111:
	s_add_u32 s22, s20, 0xfff80080
	s_addc_u32 s23, s21, -1
	s_add_i32 s76, 0, 0x10000
	s_cmp_eq_u32 vcc_lo, 28
	s_cselect_b32 s25, s15, s23
	s_cselect_b32 s24, s26, s22
	s_cselect_b32 s23, s13, s29
	s_cselect_b32 s22, s27, s28
	s_cmp_gt_i32 vcc_lo, 6
	s_cbranch_scc1 .Lmy_ip_skip
	s_cmp_lt_i32 vcc_lo, 0
	s_cbranch_scc1 .Lmy_ip_noconsume
	v_add_f32_e32 v248, v248, v249
	v_add_f32_e32 v250, v250, v251
	v_add_f32_e32 v248, v248, v250
	s_nop 1
	v_add_f32_dpp v248, v248, v248 quad_perm:[1,0,3,2] row_mask:0xf bank_mask:0xf
	s_nop 1
	v_add_f32_dpp v248, v248, v248 quad_perm:[2,3,0,1] row_mask:0xf bank_mask:0xf
	s_nop 1
	v_add_f32_dpp v248, v248, v248 row_half_mirror row_mask:0xf bank_mask:0xf
	v_fmamk_f32 v248, v248, 0x3a000000, v189
	v_rsq_f32_e32 v248, v248
	v_lshrrev_b32_e32 v252, 3, v212
	v_lshlrev_b32_e32 v252, 2, v252
	v_mov_b32_e32 v214, s3
	v_lshl_add_u32 v252, v214, 1, v252
	v_mov_b32_e32 v214, vcc_lo
	v_lshl_add_u32 v252, v214, 4, v252
	v_add_u32_e32 v252, 0x20000, v252
	ds_write_b32 v252, v248
.Lmy_ip_noconsume:
	s_cmp_gt_i32 vcc_lo, 4
	s_cbranch_scc1 .Lmy_ip_skip
	v_lshrrev_b32_e32 v252, 3, v212
	v_lshl_add_u32 v252, s4, 8, v252
	v_mov_b32_e32 v214, s3
	v_lshrrev_b32_e32 v214, 1, v214
	v_add_u32_e32 v252, v252, v214
	v_lshlrev_b32_e32 v252, 7, v252
	v_and_b32_e32 v214, 7, v212
	v_lshl_add_u32 v252, v214, 4, v252
	v_lshrrev_b32_e32 v214, 4, v212
	v_lshlrev_b32_e32 v214, 5, v214
	v_sub_u32_e32 v252, v252, v214
	v_mov_b32_e32 v214, vcc_lo
	v_add_u32_e32 v214, 2, v214
	v_lshl_add_u32 v252, v214, 9, v252
	v_mov_b32_e32 v248, v252
	v_ashrrev_i32_e32 v249, 31, v248
	v_lshl_add_u64 v[248:249], v[248:249], 0, v[154:155]
	global_load_dwordx4 v[248:251], v[248:249], off
.Lmy_ip_skip:
	s_add_i32 vcc_hi, 0, 0x14000
	v_add_u32_e32 v142, s76, v179
	v_add_u32_e32 v158, vcc_hi, v179
	ds_read_b128 v[130:133], v142
	ds_read_b128 v[134:137], v142 offset:1024
	ds_read_b128 v[138:141], v142 offset:2048
	ds_read_b128 v[142:145], v142 offset:3072
	ds_read_b128 v[172:175], v158
	ds_read_b128 v[190:193], v158 offset:1024
	ds_read_b128 v[196:199], v158 offset:2048
	ds_read_b128 v[202:205], v158 offset:3072
	v_lshl_add_u64 v[158:159], s[20:21], 0, v[164:165]
	s_add_i32 m0, s35, 0xc000
	ds_read_b128 v[216:219], v185
	ds_read_b128 v[220:223], v185 offset:1024
	ds_read_b128 v[224:227], v185 offset:2048
	ds_read_b128 v[228:231], v185 offset:3072
	ds_read_b128 v[232:235], v185 offset:4096
	ds_read_b128 v[236:239], v185 offset:5120
	ds_read_b128 v[240:243], v185 offset:6144
	ds_read_b128 v[244:247], v185 offset:7168
	global_load_lds_dwordx4 v[158:159], off
	v_lshl_add_u64 v[158:159], s[20:21], 0, v[166:167]
	s_add_i32 m0, s35, 0xe000
	s_nop 0
	global_load_lds_dwordx4 v[158:159], off
	s_waitcnt vmcnt(8)
	s_waitcnt lgkmcnt(0)
	s_barrier
	s_setprio 1
	s_waitcnt lgkmcnt(0)
	v_mfma_f32_16x16x32_bf16 v[126:129], v[130:133], v[216:219], v[126:129]
	v_mfma_f32_16x16x32_bf16 v[122:125], v[138:141], v[216:219], v[122:125]
	v_mfma_f32_16x16x32_bf16 v[110:113], v[130:133], v[224:227], v[110:113]
	v_mfma_f32_16x16x32_bf16 v[106:109], v[138:141], v[224:227], v[106:109]
	v_mfma_f32_16x16x32_bf16 v[94:97], v[130:133], v[232:235], v[94:97]
	v_mfma_f32_16x16x32_bf16 v[90:93], v[138:141], v[232:235], v[90:93]
	v_mfma_f32_16x16x32_bf16 v[78:81], v[130:133], v[240:243], v[78:81]
	v_mfma_f32_16x16x32_bf16 v[74:77], v[138:141], v[240:243], v[74:77]
	v_mfma_f32_16x16x32_bf16 v[126:129], v[134:137], v[220:223], v[126:129]
	v_mfma_f32_16x16x32_bf16 v[122:125], v[142:145], v[220:223], v[122:125]
	v_mfma_f32_16x16x32_bf16 v[110:113], v[134:137], v[228:231], v[110:113]
	v_mfma_f32_16x16x32_bf16 v[106:109], v[142:145], v[228:231], v[106:109]
	v_mfma_f32_16x16x32_bf16 v[94:97], v[134:137], v[236:239], v[94:97]
	v_mfma_f32_16x16x32_bf16 v[90:93], v[142:145], v[236:239], v[90:93]
	v_mfma_f32_16x16x32_bf16 v[78:81], v[134:137], v[244:247], v[78:81]
	v_mfma_f32_16x16x32_bf16 v[74:77], v[142:145], v[244:247], v[74:77]
	s_setprio 0
	s_setprio 1
	v_mfma_f32_16x16x32_bf16 v[118:121], v[172:175], v[216:219], v[118:121]
	v_mfma_f32_16x16x32_bf16 v[114:117], v[196:199], v[216:219], v[114:117]
	v_mfma_f32_16x16x32_bf16 v[102:105], v[172:175], v[224:227], v[102:105]
	v_mfma_f32_16x16x32_bf16 v[98:101], v[196:199], v[224:227], v[98:101]
	v_mfma_f32_16x16x32_bf16 v[86:89], v[172:175], v[232:235], v[86:89]
	v_mfma_f32_16x16x32_bf16 v[82:85], v[196:199], v[232:235], v[82:85]
	v_mfma_f32_16x16x32_bf16 v[70:73], v[172:175], v[240:243], v[70:73]
	v_mfma_f32_16x16x32_bf16 v[66:69], v[196:199], v[240:243], v[66:69]
	v_mfma_f32_16x16x32_bf16 v[118:121], v[190:193], v[220:223], v[118:121]
	v_mfma_f32_16x16x32_bf16 v[114:117], v[202:205], v[220:223], v[114:117]
	v_mfma_f32_16x16x32_bf16 v[102:105], v[190:193], v[228:231], v[102:105]
	v_mfma_f32_16x16x32_bf16 v[98:101], v[202:205], v[228:231], v[98:101]
	v_mfma_f32_16x16x32_bf16 v[86:89], v[190:193], v[236:239], v[86:89]
	v_mfma_f32_16x16x32_bf16 v[82:85], v[202:205], v[236:239], v[82:85]
	v_mfma_f32_16x16x32_bf16 v[70:73], v[190:193], v[244:247], v[70:73]
	v_mfma_f32_16x16x32_bf16 v[66:69], v[202:205], v[244:247], v[66:69]
	s_setprio 0
	s_barrier
; #define PG8_STAGE(bufoff, gbase, voff) do { _Pragma("unroll") for (int _i = 0; _i < 2; ++_i) \
;         __builtin_amdgcn_global_load_lds((const unsigned*)((const char*)(gbase) + (voff)[_i]), (PG8_LAS unsigned*)(lds + (bufoff) + ldsw + _i * 8192), 16, 0, 0); } while (0)
; #define PG8_LDA(dst, b, h) do { _Pragma("unroll") for (int m = 0; m < 4; ++m) _Pragma("unroll") for (int k = 0; k < 2; ++k) dst[m][k] = *(const PG8_LAS bf16x8*)(lds + PG8_SA(b, h) + aoff + m * 2048 + k * 1024); } while (0)
; #define PG8_LDB(dst, b, h) do { _Pragma("unroll") for (int n = 0; n < 2; ++n) _Pragma("unroll") for (int k = 0; k < 2; ++k) dst[n][k] = *(const PG8_LAS bf16x8*)(lds + PG8_SB(b, h) + boff + n * 2048 + k * 1024); } while (0)
; #define PG8_MMA(ai, bj, At, Bt) do { __builtin_amdgcn_s_setprio(1); _Pragma("unroll") for (int m = 0; m < 4; ++m) _Pragma("unroll") for (int n = 0; n < 2; ++n) _Pragma("unroll") for (int k = 0; k < 2; ++k) \
;         acc[ai][bj][m][n] = __builtin_amdgcn_mfma_f32_16x16x32_bf16(Bt[n][k], At[m][k], acc[ai][bj][m][n], 0, 0, 0); __builtin_amdgcn_s_setprio(0); } while (0)
; #define PG8_WAIT_V(n) asm volatile("s_waitcnt vmcnt(" #n ")" ::: "memory")
; #define PG8_WAIT_L(n) asm volatile("s_waitcnt lgkmcnt(" #n ")" ::: "memory")
; #define PG8_BAR __builtin_amdgcn_s_barrier()
; #define PG8_SCHED __builtin_amdgcn_sched_barrier(0)
; template <class Epi, class Sched, bool ALIGN_EPI = false, bool SP2 = false>
; __device__ __forceinline__ void gemm_phase(PG8_LAS unsigned char* lds, const Gemm g, const Sched& S, const Epi& E, const int wave_s) {
;     ...
;             PG8_LDA(At, 0, 1); PG8_STAGE(PG8_SB(0, 0), b2, voffB); PG8_STAGE(PG8_SB(0, 1), b2 + hstep, voffB); PG8_STAGE(PG8_SA(0, 0), a2, voffA);
;             PG8_WAIT_V(8); PG8_WAIT_L(0); PG8_BAR; PG8_MMA(1, 0, At, B0); PG8_MMA(1, 1, At, B1); PG8_BAR; PG8_SCHED;
;             PG8_LDB(B0, 1, 0); PG8_LDB(B1, 1, 1); PG8_SCHED; PG8_LDA(At, 1, 0); PG8_STAGE(PG8_SA(0, 1), a2 + hstep, voffA);
	s_add_i32 s76, s76, s40
	v_lshl_add_u64 v[158:159], s[22:23], 0, v[150:151]
	s_mov_b32 m0, s76
	ds_read_b128 v[216:219], v185 offset:16384
	ds_read_b128 v[220:223], v185 offset:17408
	ds_read_b128 v[224:227], v185 offset:18432
	ds_read_b128 v[228:231], v185 offset:19456
	ds_read_b128 v[232:235], v185 offset:20480
	ds_read_b128 v[236:239], v185 offset:21504
	ds_read_b128 v[240:243], v185 offset:22528
	ds_read_b128 v[244:247], v185 offset:23552
	global_load_lds_dwordx4 v[158:159], off
	s_add_i32 m0, s76, 0x2000
	s_add_u32 s76, s22, 0x80000
	v_lshl_add_u64 v[160:161], s[22:23], 0, v[146:147]
	s_addc_u32 s77, s23, 0
	s_add_i32 vcc_hi, vcc_hi, s40
	global_load_lds_dwordx4 v[160:161], off
	v_lshl_add_u64 v[168:169], s[76:77], 0, v[150:151]
	s_mov_b32 m0, vcc_hi
	v_lshl_add_u64 v[176:177], s[24:25], 0, v[148:149]
	global_load_lds_dwordx4 v[168:169], off
	v_lshl_add_u64 v[168:169], s[76:77], 0, v[146:147]
	s_add_i32 m0, vcc_hi, 0x2000
	s_nop 0
	global_load_lds_dwordx4 v[168:169], off
	v_lshl_add_u64 v[168:169], s[24:25], 0, v[152:153]
	s_mov_b32 m0, s35
	s_nop 0
	global_load_lds_dwordx4 v[168:169], off
	s_mov_b32 m0, s79
	s_nop 0
	global_load_lds_dwordx4 v[176:177], off
	s_waitcnt vmcnt(8)
	s_waitcnt lgkmcnt(0)
	s_barrier
	s_setprio 1
	s_waitcnt lgkmcnt(0)
	v_mfma_f32_16x16x32_bf16 v[62:65], v[130:133], v[216:219], v[62:65]
	v_mfma_f32_16x16x32_bf16 v[58:61], v[138:141], v[216:219], v[58:61]
	v_mfma_f32_16x16x32_bf16 v[46:49], v[130:133], v[224:227], v[46:49]
	v_mfma_f32_16x16x32_bf16 v[42:45], v[138:141], v[224:227], v[42:45]
	v_mfma_f32_16x16x32_bf16 v[30:33], v[130:133], v[232:235], v[30:33]
	v_mfma_f32_16x16x32_bf16 v[26:29], v[138:141], v[232:235], v[26:29]
	v_mfma_f32_16x16x32_bf16 v[14:17], v[130:133], v[240:243], v[14:17]
	v_mfma_f32_16x16x32_bf16 v[10:13], v[138:141], v[240:243], v[10:13]
	v_mfma_f32_16x16x32_bf16 v[62:65], v[134:137], v[220:223], v[62:65]
	v_mfma_f32_16x16x32_bf16 v[58:61], v[142:145], v[220:223], v[58:61]
	v_mfma_f32_16x16x32_bf16 v[46:49], v[134:137], v[228:231], v[46:49]
	v_mfma_f32_16x16x32_bf16 v[42:45], v[142:145], v[228:231], v[42:45]
	v_mfma_f32_16x16x32_bf16 v[30:33], v[134:137], v[236:239], v[30:33]
	v_mfma_f32_16x16x32_bf16 v[26:29], v[142:145], v[236:239], v[26:29]
	v_mfma_f32_16x16x32_bf16 v[14:17], v[134:137], v[244:247], v[14:17]
	v_mfma_f32_16x16x32_bf16 v[10:13], v[142:145], v[244:247], v[10:13]
	s_setprio 0
	s_setprio 1
	v_mfma_f32_16x16x32_bf16 v[54:57], v[172:175], v[216:219], v[54:57]
	v_mfma_f32_16x16x32_bf16 v[50:53], v[196:199], v[216:219], v[50:53]
	v_mfma_f32_16x16x32_bf16 v[38:41], v[172:175], v[224:227], v[38:41]
	v_mfma_f32_16x16x32_bf16 v[34:37], v[196:199], v[224:227], v[34:37]
	v_mfma_f32_16x16x32_bf16 v[22:25], v[172:175], v[232:235], v[22:25]
	v_mfma_f32_16x16x32_bf16 v[18:21], v[196:199], v[232:235], v[18:21]
	v_mfma_f32_16x16x32_bf16 v[6:9], v[172:175], v[240:243], v[6:9]
	v_mfma_f32_16x16x32_bf16 v[2:5], v[196:199], v[240:243], v[2:5]
	v_mfma_f32_16x16x32_bf16 v[54:57], v[190:193], v[220:223], v[54:57]
	v_mfma_f32_16x16x32_bf16 v[50:53], v[202:205], v[220:223], v[50:53]
	v_mfma_f32_16x16x32_bf16 v[38:41], v[190:193], v[228:231], v[38:41]
	v_mfma_f32_16x16x32_bf16 v[34:37], v[202:205], v[228:231], v[34:37]
	v_mfma_f32_16x16x32_bf16 v[22:25], v[190:193], v[236:239], v[22:25]
	v_mfma_f32_16x16x32_bf16 v[18:21], v[202:205], v[236:239], v[18:21]
	v_mfma_f32_16x16x32_bf16 v[6:9], v[190:193], v[244:247], v[6:9]
	v_mfma_f32_16x16x32_bf16 v[2:5], v[202:205], v[244:247], v[2:5]
	s_setprio 0
	s_barrier
	s_add_i32 s76, 0, 0x18000
	s_add_i32 s77, 0, 0x1c000
	v_add_u32_e32 v142, s76, v179
	v_add_u32_e32 v170, s77, v179
	ds_read_b128 v[130:133], v142
	ds_read_b128 v[134:137], v142 offset:1024
	ds_read_b128 v[138:141], v142 offset:2048
	ds_read_b128 v[142:145], v142 offset:3072
	ds_read_b128 v[172:175], v170
	ds_read_b128 v[190:193], v170 offset:1024
	ds_read_b128 v[196:199], v170 offset:2048
	ds_read_b128 v[202:205], v170 offset:3072
	s_add_u32 s24, s24, 0x80000
	s_addc_u32 s25, s25, 0
	s_mov_b32 m0, s43
	v_lshl_add_u64 v[182:183], s[24:25], 0, v[152:153]
	ds_read_b128 v[216:219], v185 offset:32768
	ds_read_b128 v[220:223], v185 offset:33792
	ds_read_b128 v[224:227], v185 offset:34816
	ds_read_b128 v[228:231], v185 offset:35840
	ds_read_b128 v[232:235], v185 offset:36864
	ds_read_b128 v[236:239], v185 offset:37888
	ds_read_b128 v[240:243], v185 offset:38912
	ds_read_b128 v[244:247], v185 offset:39936
	global_load_lds_dwordx4 v[182:183], off
	v_lshl_add_u64 v[182:183], s[24:25], 0, v[148:149]
	s_mov_b32 m0, s44
	s_nop 0
	global_load_lds_dwordx4 v[182:183], off
	s_waitcnt vmcnt(8)
	s_waitcnt lgkmcnt(0)
	s_barrier
; #define PG8_STAGE(bufoff, gbase, voff) do { _Pragma("unroll") for (int _i = 0; _i < 2; ++_i) \
;         __builtin_amdgcn_global_load_lds((const unsigned*)((const char*)(gbase) + (voff)[_i]), (PG8_LAS unsigned*)(lds + (bufoff) + ldsw + _i * 8192), 16, 0, 0); } while (0)
; #define PG8_LDA(dst, b, h) do { _Pragma("unroll") for (int m = 0; m < 4; ++m) _Pragma("unroll") for (int k = 0; k < 2; ++k) dst[m][k] = *(const PG8_LAS bf16x8*)(lds + PG8_SA(b, h) + aoff + m * 2048 + k * 1024); } while (0)
; #define PG8_LDB(dst, b, h) do { _Pragma("unroll") for (int n = 0; n < 2; ++n) _Pragma("unroll") for (int k = 0; k < 2; ++k) dst[n][k] = *(const PG8_LAS bf16x8*)(lds + PG8_SB(b, h) + boff + n * 2048 + k * 1024); } while (0)
; #define PG8_MMA(ai, bj, At, Bt) do { __builtin_amdgcn_s_setprio(1); _Pragma("unroll") for (int m = 0; m < 4; ++m) _Pragma("unroll") for (int n = 0; n < 2; ++n) _Pragma("unroll") for (int k = 0; k < 2; ++k) \
;         acc[ai][bj][m][n] = __builtin_amdgcn_mfma_f32_16x16x32_bf16(Bt[n][k], At[m][k], acc[ai][bj][m][n], 0, 0, 0); __builtin_amdgcn_s_setprio(0); } while (0)
; #define PG8_WAIT_V(n) asm volatile("s_waitcnt vmcnt(" #n ")" ::: "memory")
; #define PG8_WAIT_L(n) asm volatile("s_waitcnt lgkmcnt(" #n ")" ::: "memory")
; #define PG8_BAR __builtin_amdgcn_s_barrier()
; #define PG8_SCHED __builtin_amdgcn_sched_barrier(0)
; template <class Epi, class Sched, bool ALIGN_EPI = false, bool SP2 = false>
; __device__ __forceinline__ void gemm_phase(PG8_LAS unsigned char* lds, const Gemm g, const Sched& S, const Epi& E, const int wave_s) {
;     ...
;             PG8_LDB(B0, 1, 0); PG8_LDB(B1, 1, 1); PG8_SCHED; PG8_LDA(At, 1, 0); PG8_STAGE(PG8_SA(0, 1), a2 + hstep, voffA);
;             PG8_WAIT_V(8); PG8_WAIT_L(0); PG8_BAR; PG8_MMA(0, 0, At, B0); PG8_MMA(0, 1, At, B1); PG8_BAR; PG8_SCHED;
;             PG8_LDA(At, 1, 1); PG8_STAGE(PG8_SB(1, 0), b3, voffB); PG8_STAGE(PG8_SB(1, 1), b3 + hstep, voffB); PG8_STAGE(PG8_SA(1, 0), a3, voffA);
;             PG8_WAIT_V(8); PG8_WAIT_L(0); PG8_BAR; PG8_MMA(1, 0, At, B0); PG8_MMA(1, 1, At, B1); PG8_BAR; PG8_SCHED;
;     ...
;         if constexpr (ALIGN_EPI) { if (wr == 0) PG8_BAR; }
	s_setprio 1
	s_waitcnt lgkmcnt(0)
	v_mfma_f32_16x16x32_bf16 v[126:129], v[130:133], v[216:219], v[126:129]
	v_mfma_f32_16x16x32_bf16 v[122:125], v[138:141], v[216:219], v[122:125]
	v_mfma_f32_16x16x32_bf16 v[110:113], v[130:133], v[224:227], v[110:113]
	v_mfma_f32_16x16x32_bf16 v[106:109], v[138:141], v[224:227], v[106:109]
	v_mfma_f32_16x16x32_bf16 v[94:97], v[130:133], v[232:235], v[94:97]
	v_mfma_f32_16x16x32_bf16 v[90:93], v[138:141], v[232:235], v[90:93]
	v_mfma_f32_16x16x32_bf16 v[78:81], v[130:133], v[240:243], v[78:81]
	v_mfma_f32_16x16x32_bf16 v[74:77], v[138:141], v[240:243], v[74:77]
	v_mfma_f32_16x16x32_bf16 v[126:129], v[134:137], v[220:223], v[126:129]
	v_mfma_f32_16x16x32_bf16 v[122:125], v[142:145], v[220:223], v[122:125]
	v_mfma_f32_16x16x32_bf16 v[110:113], v[134:137], v[228:231], v[110:113]
	v_mfma_f32_16x16x32_bf16 v[106:109], v[142:145], v[228:231], v[106:109]
	v_mfma_f32_16x16x32_bf16 v[94:97], v[134:137], v[236:239], v[94:97]
	v_mfma_f32_16x16x32_bf16 v[90:93], v[142:145], v[236:239], v[90:93]
	v_mfma_f32_16x16x32_bf16 v[78:81], v[134:137], v[244:247], v[78:81]
	v_mfma_f32_16x16x32_bf16 v[74:77], v[142:145], v[244:247], v[74:77]
	s_setprio 0
	s_setprio 1
	v_mfma_f32_16x16x32_bf16 v[118:121], v[172:175], v[216:219], v[118:121]
	v_mfma_f32_16x16x32_bf16 v[114:117], v[196:199], v[216:219], v[114:117]
	v_mfma_f32_16x16x32_bf16 v[102:105], v[172:175], v[224:227], v[102:105]
	v_mfma_f32_16x16x32_bf16 v[98:101], v[196:199], v[224:227], v[98:101]
	v_mfma_f32_16x16x32_bf16 v[86:89], v[172:175], v[232:235], v[86:89]
	v_mfma_f32_16x16x32_bf16 v[82:85], v[196:199], v[232:235], v[82:85]
	v_mfma_f32_16x16x32_bf16 v[70:73], v[172:175], v[240:243], v[70:73]
	v_mfma_f32_16x16x32_bf16 v[66:69], v[196:199], v[240:243], v[66:69]
	v_mfma_f32_16x16x32_bf16 v[118:121], v[190:193], v[220:223], v[118:121]
	v_mfma_f32_16x16x32_bf16 v[114:117], v[202:205], v[220:223], v[114:117]
	v_mfma_f32_16x16x32_bf16 v[102:105], v[190:193], v[228:231], v[102:105]
	v_mfma_f32_16x16x32_bf16 v[98:101], v[202:205], v[228:231], v[98:101]
	v_mfma_f32_16x16x32_bf16 v[86:89], v[190:193], v[236:239], v[86:89]
	v_mfma_f32_16x16x32_bf16 v[82:85], v[202:205], v[236:239], v[82:85]
	v_mfma_f32_16x16x32_bf16 v[70:73], v[190:193], v[244:247], v[70:73]
	v_mfma_f32_16x16x32_bf16 v[66:69], v[202:205], v[244:247], v[66:69]
	s_setprio 0
	s_barrier
	s_add_i32 s24, s76, s40
	v_lshl_add_u64 v[158:159], v[158:159], 0, s[92:93]
	s_mov_b32 m0, s24
	ds_read_b128 v[216:219], v185 offset:49152
	ds_read_b128 v[220:223], v185 offset:50176
	ds_read_b128 v[224:227], v185 offset:51200
	ds_read_b128 v[228:231], v185 offset:52224
	ds_read_b128 v[232:235], v185 offset:53248
	ds_read_b128 v[236:239], v185 offset:54272
	ds_read_b128 v[240:243], v185 offset:55296
	ds_read_b128 v[244:247], v185 offset:56320
	global_load_lds_dwordx4 v[158:159], off
	s_add_i32 m0, s24, 0x2000
	s_add_u32 s22, s22, 0x80080
	v_lshl_add_u64 v[158:159], v[160:161], 0, s[92:93]
	s_addc_u32 s23, s23, 0
	s_add_i32 s24, s77, s40
	global_load_lds_dwordx4 v[158:159], off
	v_lshl_add_u64 v[158:159], s[22:23], 0, v[150:151]
	s_mov_b32 m0, s24
	s_nop 0
	global_load_lds_dwordx4 v[158:159], off
	v_lshl_add_u64 v[158:159], s[22:23], 0, v[146:147]
	s_add_i32 m0, s24, 0x2000
	s_nop 0
	global_load_lds_dwordx4 v[158:159], off
	v_lshl_add_u64 v[158:159], v[168:169], 0, s[92:93]
	s_mov_b32 m0, s62
	s_nop 0
	global_load_lds_dwordx4 v[158:159], off
	v_lshl_add_u64 v[158:159], v[176:177], 0, s[92:93]
	s_mov_b32 m0, s63
	s_nop 0
	global_load_lds_dwordx4 v[158:159], off
	s_waitcnt vmcnt(8)
	s_waitcnt lgkmcnt(0)
	s_barrier
	s_setprio 1
	s_waitcnt lgkmcnt(0)
	v_mfma_f32_16x16x32_bf16 v[62:65], v[130:133], v[216:219], v[62:65]
	v_mfma_f32_16x16x32_bf16 v[58:61], v[138:141], v[216:219], v[58:61]
	v_mfma_f32_16x16x32_bf16 v[46:49], v[130:133], v[224:227], v[46:49]
	v_mfma_f32_16x16x32_bf16 v[42:45], v[138:141], v[224:227], v[42:45]
	v_mfma_f32_16x16x32_bf16 v[30:33], v[130:133], v[232:235], v[30:33]
	v_mfma_f32_16x16x32_bf16 v[26:29], v[138:141], v[232:235], v[26:29]
	v_mfma_f32_16x16x32_bf16 v[14:17], v[130:133], v[240:243], v[14:17]
	v_mfma_f32_16x16x32_bf16 v[10:13], v[138:141], v[240:243], v[10:13]
	v_mfma_f32_16x16x32_bf16 v[62:65], v[134:137], v[220:223], v[62:65]
	v_mfma_f32_16x16x32_bf16 v[58:61], v[142:145], v[220:223], v[58:61]
	v_mfma_f32_16x16x32_bf16 v[46:49], v[134:137], v[228:231], v[46:49]
	v_mfma_f32_16x16x32_bf16 v[42:45], v[142:145], v[228:231], v[42:45]
	v_mfma_f32_16x16x32_bf16 v[30:33], v[134:137], v[236:239], v[30:33]
	v_mfma_f32_16x16x32_bf16 v[26:29], v[142:145], v[236:239], v[26:29]
	v_mfma_f32_16x16x32_bf16 v[14:17], v[134:137], v[244:247], v[14:17]
	v_mfma_f32_16x16x32_bf16 v[10:13], v[142:145], v[244:247], v[10:13]
	s_setprio 0
	s_setprio 1
	v_mfma_f32_16x16x32_bf16 v[54:57], v[172:175], v[216:219], v[54:57]
	v_mfma_f32_16x16x32_bf16 v[50:53], v[196:199], v[216:219], v[50:53]
	v_mfma_f32_16x16x32_bf16 v[38:41], v[172:175], v[224:227], v[38:41]
	v_mfma_f32_16x16x32_bf16 v[34:37], v[196:199], v[224:227], v[34:37]
	v_mfma_f32_16x16x32_bf16 v[22:25], v[172:175], v[232:235], v[22:25]
	v_mfma_f32_16x16x32_bf16 v[18:21], v[196:199], v[232:235], v[18:21]
	v_mfma_f32_16x16x32_bf16 v[6:9], v[172:175], v[240:243], v[6:9]
	v_mfma_f32_16x16x32_bf16 v[2:5], v[196:199], v[240:243], v[2:5]
	v_mfma_f32_16x16x32_bf16 v[54:57], v[190:193], v[220:223], v[54:57]
	v_mfma_f32_16x16x32_bf16 v[50:53], v[202:205], v[220:223], v[50:53]
	v_mfma_f32_16x16x32_bf16 v[38:41], v[190:193], v[228:231], v[38:41]
	v_mfma_f32_16x16x32_bf16 v[34:37], v[202:205], v[228:231], v[34:37]
	v_mfma_f32_16x16x32_bf16 v[22:25], v[190:193], v[236:239], v[22:25]
	v_mfma_f32_16x16x32_bf16 v[18:21], v[202:205], v[236:239], v[18:21]
	v_mfma_f32_16x16x32_bf16 v[6:9], v[190:193], v[244:247], v[6:9]
	v_mfma_f32_16x16x32_bf16 v[2:5], v[202:205], v[244:247], v[2:5]
	s_setprio 0
	s_barrier
	s_add_i32 vcc_lo, vcc_lo, 2
	s_add_u32 s20, s20, 0x100
	s_addc_u32 s21, s21, 0
	s_add_u32 s28, s28, 0x100
	s_addc_u32 s29, s29, 0
	s_cmp_gt_u32 vcc_lo, 29
	s_cbranch_scc0 .LBB0_111
	s_and_b64 vcc, exec, s[10:11]
	s_cbranch_vccz .LBB0_114
	s_barrier

; __device__ __forceinline__ unsigned cvt_pk_bf16(float lo, float hi) { f32x2 v = {lo, hi}; bf16x2_t b = __builtin_convertvector(v, bf16x2_t); return __builtin_bit_cast(unsigned, b); }
;     __device__ __forceinline__ void operator()(const f32x4 (&acc)[2][2][4][2], const Unit& u, int wr, int wc, int fr, int fq) const {
;     ...
;         const int row0 = u.pm * BM + wr * 64 + fr;
;         float rs[2][4];
; #pragma unroll
;         for (int ai = 0; ai < 2; ++ai)
; #pragma unroll
;             for (int m = 0; m < 4; ++m) rs[ai][m] = row_rstd(rowss, row0 + ai * HALF + m * 16, fq);
;     ...
;             const int col0 = colt + wc * 32 + 8 * fq;
; #pragma unroll
;             for (int ai = 0; ai < 2; ++ai)
; #pragma unroll
;                 for (int m = 0; m < 4; ++m) { bf16_t* rowp = dst + (size_t)(row0 + ai * HALF + m * 16) * ldc + col0; const float r_ = rs[ai][m];
; #pragma unroll
;                     for (int bj = 0; bj < 2; ++bj) { const f32x4 v0 = acc[ai][bj][m][0] * r_, v1 = acc[ai][bj][m][1] * r_;
;                         u32x4 w; w.x = cvt_pk_bf16(v0[0], v0[1]); w.y = cvt_pk_bf16(v0[2], v0[3]); w.z = cvt_pk_bf16(v1[0], v1[1]); w.w = cvt_pk_bf16(v1[2], v1[3]);
;                         *(u32x4*)(rowp + bj * HALF) = w; } }
.LBB0_121:
	v_and_b32_e32 v131, 64, v212
	v_xor_b32_e32 v130, 16, v212
	v_add_u32_e32 v131, 64, v131
	v_cmp_lt_i32_e32 vcc, v130, v131
	v_lshl_add_u32 v172, s4, 8, v171
	v_ashrrev_i32_e32 v173, 31, v172
	v_cndmask_b32_e32 v130, v212, v130, vcc
	v_lshlrev_b32_e32 v145, 2, v130
	v_xor_b32_e32 v130, 32, v212
	v_cmp_lt_i32_e32 vcc, v130, v131
	v_lshlrev_b64 v[138:139], 7, v[172:173]
	v_lshl_add_u64 v[134:135], v[154:155], 0, v[138:139]
	v_cndmask_b32_e32 v130, v212, v130, vcc
	v_lshlrev_b32_e32 v144, 2, v130
	v_or_b32_e32 v174, 16, v172
	v_ashrrev_i32_e32 v175, 31, v174
	v_lshlrev_b64 v[140:141], 7, v[174:175]
	v_or_b32_e32 v168, 32, v172
	v_ashrrev_i32_e32 v169, 31, v168
	v_lshlrev_b64 v[142:143], 7, v[168:169]
	v_or_b32_e32 v176, 48, v172
	v_ashrrev_i32_e32 v177, 31, v176
	v_lshlrev_b64 v[190:191], 7, v[176:177]
	v_add_u32_e32 v182, 0x80, v172
	v_ashrrev_i32_e32 v183, 31, v182
	v_lshlrev_b64 v[186:187], 7, v[182:183]
	v_add_u32_e32 v192, 0x90, v172
	v_ashrrev_i32_e32 v193, 31, v192
	v_lshlrev_b64 v[196:197], 7, v[192:193]
	v_add_u32_e32 v198, 0xa0, v172
	v_ashrrev_i32_e32 v199, 31, v198
	v_lshlrev_b64 v[202:203], 7, v[198:199]
	v_add_u32_e32 v204, 0xb0, v172
	v_ashrrev_i32_e32 v205, 31, v204
	v_lshlrev_b64 v[206:207], 7, v[204:205]
	v_mul_lo_u32 v223, s21, v172
	v_mul_lo_u32 v224, s20, v173
	v_mul_lo_u32 v221, s21, v174
	v_mul_lo_u32 v222, s20, v175
	v_mul_lo_u32 v219, s21, v168
	v_mul_lo_u32 v220, s20, v169
	v_mul_lo_u32 v217, s21, v176
	v_mul_lo_u32 v218, s20, v177
	v_mul_lo_u32 v215, s21, v182
	v_mul_lo_u32 v216, s20, v183
	v_mul_lo_u32 v183, s21, v192
	v_mul_lo_u32 v193, s20, v193
	v_mul_lo_u32 v175, s21, v198
	v_mul_lo_u32 v177, s20, v199
	v_mul_lo_u32 v169, s21, v204
	v_mul_lo_u32 v173, s20, v205
	v_lshlrev_b32_e32 v130, 2, v171
	v_add_u32_e32 v130, 0x20000, v130
	ds_read_b32 v178, v130
	ds_read_b32 v184, v130 offset:64
	ds_read_b32 v170, v130 offset:128
	ds_read_b32 v180, v130 offset:192
	ds_read_b32 v188, v130 offset:512
	ds_read_b32 v194, v130 offset:576
	ds_read_b32 v200, v130 offset:640
	ds_read_b32 v208, v130 offset:704
	s_waitcnt lgkmcnt(0)
	s_mov_b64 s[4:5], -1
	s_andn2_b64 vcc, exec, s[26:27]
	s_cbranch_vccz .LBB0_124
	v_or_b32_e32 v130, s24, v181
	v_ashrrev_i32_e32 v131, 31, v130
	v_mad_u64_u32 v[132:133], s[4:5], s20, v172, 0
	v_lshl_add_u64 v[130:131], v[130:131], 1, s[22:23]
	v_add3_u32 v133, v133, v224, v223
	v_lshl_add_u64 v[136:137], v[132:133], 1, v[130:131]
	v_pk_mul_f32 v[134:135], v[128:129], v[178:179] op_sel_hi:[1,0]
	v_pk_mul_f32 v[132:133], v[126:127], v[178:179] op_sel_hi:[1,0]
	v_pk_mul_f32 v[144:145], v[124:125], v[178:179] op_sel_hi:[1,0]
	v_pk_mul_f32 v[158:159], v[122:123], v[178:179] op_sel_hi:[1,0]
	v_cvt_pk_bf16_f32 v132, v132, v133
	v_cvt_pk_bf16_f32 v133, v134, v135
	v_cvt_pk_bf16_f32 v134, v158, v159
	v_cvt_pk_bf16_f32 v135, v144, v145
	global_store_dwordx4 v[136:137], v[132:135], off
	v_pk_mul_f32 v[144:145], v[116:117], v[178:179] op_sel_hi:[1,0]
	v_pk_mul_f32 v[158:159], v[114:115], v[178:179] op_sel_hi:[1,0]
	v_pk_mul_f32 v[134:135], v[120:121], v[178:179] op_sel_hi:[1,0]
	v_pk_mul_f32 v[132:133], v[118:119], v[178:179] op_sel_hi:[1,0]
	s_nop 0
	v_cvt_pk_bf16_f32 v132, v132, v133
	v_cvt_pk_bf16_f32 v133, v134, v135
	v_cvt_pk_bf16_f32 v134, v158, v159
	v_cvt_pk_bf16_f32 v135, v144, v145
	global_store_dwordx4 v[136:137], v[132:135], off offset:256
	v_pk_mul_f32 v[144:145], v[108:109], v[184:185] op_sel_hi:[1,0]
	v_pk_mul_f32 v[158:159], v[106:107], v[184:185] op_sel_hi:[1,0]
	v_mad_u64_u32 v[132:133], s[4:5], s20, v174, 0
	v_add3_u32 v133, v133, v222, v221
	v_lshl_add_u64 v[136:137], v[132:133], 1, v[130:131]
	v_pk_mul_f32 v[134:135], v[112:113], v[184:185] op_sel_hi:[1,0]
	v_pk_mul_f32 v[132:133], v[110:111], v[184:185] op_sel_hi:[1,0]
	s_nop 0
	v_cvt_pk_bf16_f32 v132, v132, v133
	v_cvt_pk_bf16_f32 v133, v134, v135
	v_cvt_pk_bf16_f32 v134, v158, v159
	v_cvt_pk_bf16_f32 v135, v144, v145
	global_store_dwordx4 v[136:137], v[132:135], off
	v_pk_mul_f32 v[144:145], v[100:101], v[184:185] op_sel_hi:[1,0]
	v_pk_mul_f32 v[158:159], v[98:99], v[184:185] op_sel_hi:[1,0]
	v_pk_mul_f32 v[134:135], v[104:105], v[184:185] op_sel_hi:[1,0]
	v_pk_mul_f32 v[132:133], v[102:103], v[184:185] op_sel_hi:[1,0]
	s_nop 0
	v_cvt_pk_bf16_f32 v132, v132, v133
	v_cvt_pk_bf16_f32 v133, v134, v135
	v_cvt_pk_bf16_f32 v134, v158, v159
	v_cvt_pk_bf16_f32 v135, v144, v145
	global_store_dwordx4 v[136:137], v[132:135], off offset:256
	v_pk_mul_f32 v[144:145], v[92:93], v[170:171] op_sel_hi:[1,0]
	v_pk_mul_f32 v[158:159], v[90:91], v[170:171] op_sel_hi:[1,0]
	v_mad_u64_u32 v[132:133], s[4:5], s20, v168, 0
	v_add3_u32 v133, v133, v220, v219
	v_lshl_add_u64 v[136:137], v[132:133], 1, v[130:131]
	v_pk_mul_f32 v[134:135], v[96:97], v[170:171] op_sel_hi:[1,0]
	v_pk_mul_f32 v[132:133], v[94:95], v[170:171] op_sel_hi:[1,0]
	s_nop 0
	v_cvt_pk_bf16_f32 v132, v132, v133
	v_cvt_pk_bf16_f32 v133, v134, v135
	v_cvt_pk_bf16_f32 v134, v158, v159
	v_cvt_pk_bf16_f32 v135, v144, v145
	global_store_dwordx4 v[136:137], v[132:135], off
	v_pk_mul_f32 v[144:145], v[84:85], v[170:171] op_sel_hi:[1,0]
	v_pk_mul_f32 v[158:159], v[82:83], v[170:171] op_sel_hi:[1,0]
	v_pk_mul_f32 v[134:135], v[88:89], v[170:171] op_sel_hi:[1,0]
	v_pk_mul_f32 v[132:133], v[86:87], v[170:171] op_sel_hi:[1,0]
	s_nop 0
	v_cvt_pk_bf16_f32 v132, v132, v133
	v_cvt_pk_bf16_f32 v133, v134, v135
	v_cvt_pk_bf16_f32 v134, v158, v159
; __device__ __forceinline__ unsigned cvt_pk_bf16(float lo, float hi) { f32x2 v = {lo, hi}; bf16x2_t b = __builtin_convertvector(v, bf16x2_t); return __builtin_bit_cast(unsigned, b); }
;     __device__ __forceinline__ void operator()(const f32x4 (&acc)[2][2][4][2], const Unit& u, int wr, int wc, int fr, int fq) const {
;     ...
;                 for (int m = 0; m < 4; ++m) { bf16_t* rowp = dst + (size_t)(row0 + ai * HALF + m * 16) * ldc + col0; const float r_ = rs[ai][m];
; #pragma unroll
;                     for (int bj = 0; bj < 2; ++bj) { const f32x4 v0 = acc[ai][bj][m][0] * r_, v1 = acc[ai][bj][m][1] * r_;
;                         u32x4 w; w.x = cvt_pk_bf16(v0[0], v0[1]); w.y = cvt_pk_bf16(v0[2], v0[3]); w.z = cvt_pk_bf16(v1[0], v1[1]); w.w = cvt_pk_bf16(v1[2], v1[3]);
;                         *(u32x4*)(rowp + bj * HALF) = w; } }
	v_cvt_pk_bf16_f32 v135, v144, v145
	global_store_dwordx4 v[136:137], v[132:135], off offset:256
	v_pk_mul_f32 v[144:145], v[76:77], v[180:181] op_sel_hi:[1,0]
	v_pk_mul_f32 v[158:159], v[74:75], v[180:181] op_sel_hi:[1,0]
	v_mad_u64_u32 v[132:133], s[4:5], s20, v176, 0
	v_add3_u32 v133, v133, v218, v217
	v_lshl_add_u64 v[136:137], v[132:133], 1, v[130:131]
	v_pk_mul_f32 v[134:135], v[80:81], v[180:181] op_sel_hi:[1,0]
	v_pk_mul_f32 v[132:133], v[78:79], v[180:181] op_sel_hi:[1,0]
	s_nop 0
	v_cvt_pk_bf16_f32 v132, v132, v133
	v_cvt_pk_bf16_f32 v133, v134, v135
	v_cvt_pk_bf16_f32 v134, v158, v159
	v_cvt_pk_bf16_f32 v135, v144, v145
	global_store_dwordx4 v[136:137], v[132:135], off
	v_pk_mul_f32 v[144:145], v[68:69], v[180:181] op_sel_hi:[1,0]
	v_pk_mul_f32 v[158:159], v[66:67], v[180:181] op_sel_hi:[1,0]
	v_pk_mul_f32 v[134:135], v[72:73], v[180:181] op_sel_hi:[1,0]
	v_pk_mul_f32 v[132:133], v[70:71], v[180:181] op_sel_hi:[1,0]
	s_nop 0
	v_cvt_pk_bf16_f32 v132, v132, v133
	v_cvt_pk_bf16_f32 v133, v134, v135
	v_cvt_pk_bf16_f32 v134, v158, v159
	v_cvt_pk_bf16_f32 v135, v144, v145
	global_store_dwordx4 v[136:137], v[132:135], off offset:256
	v_pk_mul_f32 v[144:145], v[60:61], v[188:189] op_sel_hi:[1,0]
	v_pk_mul_f32 v[158:159], v[58:59], v[188:189] op_sel_hi:[1,0]
	v_mad_u64_u32 v[132:133], s[4:5], s20, v182, 0
	v_add3_u32 v133, v133, v216, v215
	v_lshl_add_u64 v[136:137], v[132:133], 1, v[130:131]
	v_pk_mul_f32 v[134:135], v[64:65], v[188:189] op_sel_hi:[1,0]
	v_pk_mul_f32 v[132:133], v[62:63], v[188:189] op_sel_hi:[1,0]
	s_nop 0
	v_cvt_pk_bf16_f32 v132, v132, v133
	v_cvt_pk_bf16_f32 v133, v134, v135
	v_cvt_pk_bf16_f32 v134, v158, v159
	v_cvt_pk_bf16_f32 v135, v144, v145
	global_store_dwordx4 v[136:137], v[132:135], off
	v_pk_mul_f32 v[144:145], v[52:53], v[188:189] op_sel_hi:[1,0]
	v_pk_mul_f32 v[158:159], v[50:51], v[188:189] op_sel_hi:[1,0]
	v_pk_mul_f32 v[134:135], v[56:57], v[188:189] op_sel_hi:[1,0]
	v_pk_mul_f32 v[132:133], v[54:55], v[188:189] op_sel_hi:[1,0]
	s_nop 0
	v_cvt_pk_bf16_f32 v132, v132, v133
	v_cvt_pk_bf16_f32 v133, v134, v135
	v_cvt_pk_bf16_f32 v134, v158, v159
	v_cvt_pk_bf16_f32 v135, v144, v145
	global_store_dwordx4 v[136:137], v[132:135], off offset:256
	v_pk_mul_f32 v[144:145], v[44:45], v[194:195] op_sel_hi:[1,0]
	v_pk_mul_f32 v[158:159], v[42:43], v[194:195] op_sel_hi:[1,0]
	v_mad_u64_u32 v[132:133], s[4:5], s20, v192, 0
	v_add3_u32 v133, v133, v193, v183
	v_lshl_add_u64 v[136:137], v[132:133], 1, v[130:131]
	v_pk_mul_f32 v[134:135], v[48:49], v[194:195] op_sel_hi:[1,0]
	v_pk_mul_f32 v[132:133], v[46:47], v[194:195] op_sel_hi:[1,0]
	s_nop 0
	v_cvt_pk_bf16_f32 v132, v132, v133
	v_cvt_pk_bf16_f32 v133, v134, v135
	v_cvt_pk_bf16_f32 v134, v158, v159
	v_cvt_pk_bf16_f32 v135, v144, v145
	global_store_dwordx4 v[136:137], v[132:135], off
	v_pk_mul_f32 v[144:145], v[36:37], v[194:195] op_sel_hi:[1,0]
	v_pk_mul_f32 v[158:159], v[34:35], v[194:195] op_sel_hi:[1,0]
	v_pk_mul_f32 v[134:135], v[40:41], v[194:195] op_sel_hi:[1,0]
	v_pk_mul_f32 v[132:133], v[38:39], v[194:195] op_sel_hi:[1,0]
	s_nop 0
	v_cvt_pk_bf16_f32 v132, v132, v133
	v_cvt_pk_bf16_f32 v133, v134, v135
	v_cvt_pk_bf16_f32 v134, v158, v159
	v_cvt_pk_bf16_f32 v135, v144, v145
	global_store_dwordx4 v[136:137], v[132:135], off offset:256
	v_pk_mul_f32 v[144:145], v[28:29], v[200:201] op_sel_hi:[1,0]
	v_pk_mul_f32 v[158:159], v[26:27], v[200:201] op_sel_hi:[1,0]
	v_mad_u64_u32 v[132:133], s[4:5], s20, v198, 0
	v_add3_u32 v133, v133, v177, v175
	v_lshl_add_u64 v[136:137], v[132:133], 1, v[130:131]
	v_pk_mul_f32 v[134:135], v[32:33], v[200:201] op_sel_hi:[1,0]
	v_pk_mul_f32 v[132:133], v[30:31], v[200:201] op_sel_hi:[1,0]
	s_nop 0
	v_cvt_pk_bf16_f32 v132, v132, v133
	v_cvt_pk_bf16_f32 v133, v134, v135
	v_cvt_pk_bf16_f32 v134, v158, v159
	v_cvt_pk_bf16_f32 v135, v144, v145
	global_store_dwordx4 v[136:137], v[132:135], off
	v_pk_mul_f32 v[144:145], v[20:21], v[200:201] op_sel_hi:[1,0]
	v_pk_mul_f32 v[158:159], v[18:19], v[200:201] op_sel_hi:[1,0]
	v_pk_mul_f32 v[134:135], v[24:25], v[200:201] op_sel_hi:[1,0]
	v_pk_mul_f32 v[132:133], v[22:23], v[200:201] op_sel_hi:[1,0]
	s_nop 0
	v_cvt_pk_bf16_f32 v132, v132, v133
	v_cvt_pk_bf16_f32 v133, v134, v135
	v_cvt_pk_bf16_f32 v134, v158, v159
	v_cvt_pk_bf16_f32 v135, v144, v145
	global_store_dwordx4 v[136:137], v[132:135], off offset:256
	v_pk_mul_f32 v[136:137], v[12:13], v[208:209] op_sel_hi:[1,0]
	v_pk_mul_f32 v[144:145], v[10:11], v[208:209] op_sel_hi:[1,0]
	v_mad_u64_u32 v[132:133], s[4:5], s20, v204, 0
	v_add3_u32 v133, v133, v173, v169
	v_lshl_add_u64 v[134:135], v[132:133], 1, v[130:131]
	v_pk_mul_f32 v[132:133], v[16:17], v[208:209] op_sel_hi:[1,0]
	v_pk_mul_f32 v[130:131], v[14:15], v[208:209] op_sel_hi:[1,0]
	s_nop 0
	v_cvt_pk_bf16_f32 v130, v130, v131
	v_cvt_pk_bf16_f32 v131, v132, v133
	v_cvt_pk_bf16_f32 v132, v144, v145
	v_cvt_pk_bf16_f32 v133, v136, v137
	global_store_dwordx4 v[134:135], v[130:133], off
	v_pk_mul_f32 v[136:137], v[4:5], v[208:209] op_sel_hi:[1,0]
	v_pk_mul_f32 v[144:145], v[2:3], v[208:209] op_sel_hi:[1,0]
	v_pk_mul_f32 v[132:133], v[8:9], v[208:209] op_sel_hi:[1,0]
	v_pk_mul_f32 v[130:131], v[6:7], v[208:209] op_sel_hi:[1,0]
	s_nop 0
	v_cvt_pk_bf16_f32 v130, v130, v131
	v_cvt_pk_bf16_f32 v131, v132, v133
	v_cvt_pk_bf16_f32 v132, v144, v145
	v_cvt_pk_bf16_f32 v133, v136, v137
	global_store_dwordx4 v[134:135], v[130:133], off offset:256
	s_cbranch_execz .LBB0_125
